# context-partials block in the norm phases: counted vmcnt waits per 1024-column slice (15/11/7/3) instead of one vmcnt(0) before all four
# speedup vs baseline: 1.0016x; 1.0016x over previous
; __device__ __forceinline__ void norm_phase(const float* xlat, const float* xctx, const float* gvec, const float* mod, int sh_off, int sc_off, bf16_t* H, int nrows,
;                                            const float* part, const float* pgate, float* xctx_out, int row_lo) {
;     ...
;         if (part != nullptr && row >= NLAT) {
; #pragma unroll
;             for (int j = 0; j < 4; ++j) {
;                 const size_t o = (size_t)(row - NLAT) * DM + 4 * lane + 256 * j;
;                 const f32x4 ps = (*(const f32x4*)(part + o) + *(const f32x4*)(part + (size_t)NCTX * DM + o)) + (*(const f32x4*)(part + (size_t)2 * NCTX * DM + o) + *(const f32x4*)(part + (size_t)3 * NCTX * DM + o));
;                 v[j] = v[j] + *(const f32x4*)(pgate + 4 * lane + 256 * j) * ps;
;                 *(f32x4*)(xctx_out + o) = v[j];
;             }
;         }
.Ln1_join:
	s_or_b64 exec, exec, s[12:13]
	s_movk_i32 s0, 0x3fff
	v_cmp_lt_i32_e64 s[0:1], s0, v97
	s_and_b64 s[12:13], s[4:5], s[0:1]
	s_and_saveexec_b64 s[0:1], s[12:13]
	s_cbranch_execz .LBB0_175
	v_mov_b32_e32 v97, v161
	v_lshlrev_b64 v[96:97], 12, v[96:97]
	v_readlane_b32 s12, v253, 18
	v_readlane_b32 s13, v253, 19
	v_lshl_or_b32 v96, v80, 2, v96
	v_mov_b32_e32 v251, v97
	v_lshl_add_u64 v[248:249], s[14:15], 0, v[96:97]
	global_load_dwordx4 v[122:125], v[248:249], off
	v_lshl_add_u64 v[248:249], s[12:13], 0, v[96:97]
	global_load_dwordx4 v[126:129], v[248:249], off
	v_lshl_add_u64 v[248:249], s[46:47], 0, v[96:97]
	global_load_dwordx4 v[130:133], v[248:249], off
	v_lshl_add_u64 v[248:249], s[66:67], 0, v[96:97]
	global_load_dwordx4 v[134:137], v[248:249], off
	global_load_dwordx4 v[138:141], v[82:83], off
	v_or_b32_e32 v250, 0x400, v96
	v_lshl_add_u64 v[248:249], s[14:15], 0, v[250:251]
	global_load_dwordx4 v[142:145], v[248:249], off
	v_lshl_add_u64 v[248:249], s[12:13], 0, v[250:251]
	global_load_dwordx4 v[146:149], v[248:249], off
	v_lshl_add_u64 v[248:249], s[46:47], 0, v[250:251]
	global_load_dwordx4 v[150:153], v[248:249], off
	v_lshl_add_u64 v[248:249], s[66:67], 0, v[250:251]
	global_load_dwordx4 v[162:165], v[248:249], off
	global_load_dwordx4 v[166:169], v[82:83], off offset:1024
	v_or_b32_e32 v250, 0x800, v96
	v_lshl_add_u64 v[248:249], s[14:15], 0, v[250:251]
	global_load_dwordx4 v[170:173], v[248:249], off
	v_lshl_add_u64 v[248:249], s[12:13], 0, v[250:251]
	global_load_dwordx4 v[174:177], v[248:249], off
	v_lshl_add_u64 v[248:249], s[46:47], 0, v[250:251]
	global_load_dwordx4 v[178:181], v[248:249], off
	v_lshl_add_u64 v[248:249], s[66:67], 0, v[250:251]
	global_load_dwordx4 v[182:185], v[248:249], off
	global_load_dwordx4 v[186:189], v[82:83], off offset:2048
	v_or_b32_e32 v250, 0xc00, v96
	v_lshl_add_u64 v[248:249], s[14:15], 0, v[250:251]
	global_load_dwordx4 v[216:219], v[248:249], off
	v_lshl_add_u64 v[248:249], s[12:13], 0, v[250:251]
	global_load_dwordx4 v[220:223], v[248:249], off
	v_lshl_add_u64 v[248:249], s[46:47], 0, v[250:251]
	global_load_dwordx4 v[224:227], v[248:249], off
	v_lshl_add_u64 v[248:249], s[66:67], 0, v[250:251]
	global_load_dwordx4 v[228:231], v[248:249], off
	global_load_dwordx4 v[232:235], v[82:83], off offset:3072
	s_waitcnt vmcnt(15)
	v_pk_add_f32 v[236:237], v[122:123], v[126:127]
	v_pk_add_f32 v[238:239], v[124:125], v[128:129]
	v_pk_add_f32 v[240:241], v[130:131], v[134:135]
	v_pk_add_f32 v[242:243], v[132:133], v[136:137]
	v_pk_add_f32 v[236:237], v[236:237], v[240:241]
	v_pk_add_f32 v[238:239], v[238:239], v[242:243]
	v_pk_fma_f32 v[14:15], v[140:141], v[238:239], v[14:15]
	v_pk_fma_f32 v[12:13], v[138:139], v[236:237], v[12:13]
	v_lshl_add_u64 v[248:249], s[26:27], 0, v[96:97]
	global_store_dwordx4 v[248:249], v[12:15], off
	s_waitcnt vmcnt(11)
	v_pk_add_f32 v[236:237], v[142:143], v[146:147]
	v_pk_add_f32 v[238:239], v[144:145], v[148:149]
	v_pk_add_f32 v[240:241], v[150:151], v[162:163]
	v_pk_add_f32 v[242:243], v[152:153], v[164:165]
	v_pk_add_f32 v[236:237], v[236:237], v[240:241]
	v_pk_add_f32 v[238:239], v[238:239], v[242:243]
	v_pk_fma_f32 v[10:11], v[168:169], v[238:239], v[10:11]
	v_pk_fma_f32 v[8:9], v[166:167], v[236:237], v[8:9]
	v_or_b32_e32 v250, 0x400, v96
	v_lshl_add_u64 v[248:249], s[26:27], 0, v[250:251]
	global_store_dwordx4 v[248:249], v[8:11], off
	s_waitcnt vmcnt(7)
	v_pk_add_f32 v[236:237], v[170:171], v[174:175]
	v_pk_add_f32 v[238:239], v[172:173], v[176:177]
	v_pk_add_f32 v[240:241], v[178:179], v[182:183]
	v_pk_add_f32 v[242:243], v[180:181], v[184:185]
	v_pk_add_f32 v[236:237], v[236:237], v[240:241]
	v_pk_add_f32 v[238:239], v[238:239], v[242:243]
	v_pk_fma_f32 v[6:7], v[188:189], v[238:239], v[6:7]
	v_pk_fma_f32 v[4:5], v[186:187], v[236:237], v[4:5]
	v_or_b32_e32 v250, 0x800, v96
	v_lshl_add_u64 v[248:249], s[26:27], 0, v[250:251]
	global_store_dwordx4 v[248:249], v[4:7], off
	s_waitcnt vmcnt(3)
	v_pk_add_f32 v[236:237], v[216:217], v[220:221]
	v_pk_add_f32 v[238:239], v[218:219], v[222:223]
	v_pk_add_f32 v[240:241], v[224:225], v[228:229]
	v_pk_add_f32 v[242:243], v[226:227], v[230:231]
	v_pk_add_f32 v[236:237], v[236:237], v[240:241]
	v_pk_add_f32 v[238:239], v[238:239], v[242:243]
	v_pk_fma_f32 v[2:3], v[234:235], v[238:239], v[2:3]
	v_pk_fma_f32 v[0:1], v[232:233], v[236:237], v[0:1]
	v_or_b32_e32 v250, 0xc00, v96
	v_lshl_add_u64 v[248:249], s[26:27], 0, v[250:251]
	global_store_dwordx4 v[248:249], v[0:3], off
	s_branch .LBB0_175

; __device__ __forceinline__ void norm_phase(const float* xlat, const float* xctx, const float* gvec, const float* mod, int sh_off, int sc_off, bf16_t* H, int nrows,
;                                            const float* part, const float* pgate, float* xctx_out, int row_lo) {
;     ...
;         const float* mp = mod + bb * 6144;
;         f32x4 gg[4], sc[4], sh[4];
; #pragma unroll
;         for (int j = 0; j < 4; ++j) { const int col = 4 * lane + 256 * j; gg[j] = *(const f32x4*)(gvec + col); sc[j] = *(const f32x4*)(mp + sc_off + col); sh[j] = *(const f32x4*)(mp + sh_off + col); }
;         if (part != nullptr && row >= NLAT) {
; #pragma unroll
;             for (int j = 0; j < 4; ++j) {
;                 const size_t o = (size_t)(row - NLAT) * DM + 4 * lane + 256 * j;
;                 const f32x4 ps = (*(const f32x4*)(part + o) + *(const f32x4*)(part + (size_t)NCTX * DM + o)) + (*(const f32x4*)(part + (size_t)2 * NCTX * DM + o) + *(const f32x4*)(part + (size_t)3 * NCTX * DM + o));
;                 v[j] = v[j] + *(const f32x4*)(pgate + 4 * lane + 256 * j) * ps;
;                 *(f32x4*)(xctx_out + o) = v[j];
;             }
;         }
.LBB0_1140:
	s_or_b64 exec, exec, s[12:13]
	v_add_u32_e32 v97, 0x4000, v96
	v_min_i32_e32 v32, 0x4000, v97
	v_ashrrev_i32_e32 v32, 11, v32
	v_mul_i32_i24_e32 v32, 0x1800, v32
	v_ashrrev_i32_e32 v33, 31, v32
	v_lshl_add_u64 v[32:33], v[32:33], 2, s[48:49]
	s_mov_b64 s[0:1], 0x4000
	v_lshl_add_u64 v[34:35], v[32:33], 0, s[0:1]
	s_mov_b64 s[0:1], 0x3000
	v_lshl_add_u64 v[32:33], v[32:33], 0, s[0:1]
	v_lshl_add_u64 v[36:37], v[34:35], 0, v[160:161]
	v_lshl_add_u64 v[38:39], v[32:33], 0, v[160:161]
	v_mov_b32_e32 v85, v161
	global_load_dwordx4 v[76:79], v[36:37], off
	global_load_dwordx4 v[68:71], v[38:39], off
	global_load_dwordx4 v[72:75], v[92:93], off
	global_load_dwordx4 v[60:63], v[92:93], off offset:1024
	v_lshl_add_u64 v[36:37], v[34:35], 0, v[84:85]
	v_lshl_add_u64 v[38:39], v[32:33], 0, v[84:85]
	v_mov_b32_e32 v87, v161
	global_load_dwordx4 v[64:67], v[36:37], off
	global_load_dwordx4 v[56:59], v[38:39], off
	v_lshl_add_u64 v[36:37], v[34:35], 0, v[86:87]
	v_lshl_add_u64 v[38:39], v[32:33], 0, v[86:87]
	global_load_dwordx4 v[48:51], v[36:37], off
	global_load_dwordx4 v[44:47], v[38:39], off
	global_load_dwordx4 v[52:55], v[92:93], off offset:2048
	s_nop 0
	global_load_dwordx4 v[36:39], v[92:93], off offset:3072
	v_mov_b32_e32 v89, v161
	v_lshl_add_u64 v[34:35], v[34:35], 0, v[88:89]
	v_lshl_add_u64 v[32:33], v[32:33], 0, v[88:89]
	global_load_dwordx4 v[40:43], v[34:35], off
	s_nop 0
	global_load_dwordx4 v[32:35], v[32:33], off
	s_movk_i32 s0, 0x3fff
	v_readlane_b32 s12, v255, 26
	v_cmp_lt_i32_e64 s[0:1], s0, v97
	v_readlane_b32 s13, v255, 27
	s_and_b64 s[12:13], s[12:13], s[0:1]
	s_and_saveexec_b64 s[0:1], s[12:13]
	s_cbranch_execz .LBB0_1137
	v_mov_b32_e32 v97, v161
	v_lshlrev_b64 v[96:97], 12, v[96:97]
	v_lshl_or_b32 v96, v80, 2, v96
	v_mov_b32_e32 v251, v97
	v_lshl_add_u64 v[248:249], s[22:23], 0, v[96:97]
	global_load_dwordx4 v[122:125], v[248:249], off
	v_lshl_add_u64 v[248:249], s[10:11], 0, v[96:97]
	global_load_dwordx4 v[126:129], v[248:249], off
	v_lshl_add_u64 v[248:249], s[46:47], 0, v[96:97]
	global_load_dwordx4 v[130:133], v[248:249], off
	v_lshl_add_u64 v[248:249], s[50:51], 0, v[96:97]
	global_load_dwordx4 v[134:137], v[248:249], off
	global_load_dwordx4 v[138:141], v[90:91], off
	v_or_b32_e32 v250, 0x400, v96
	v_lshl_add_u64 v[248:249], s[22:23], 0, v[250:251]
	global_load_dwordx4 v[142:145], v[248:249], off
	v_lshl_add_u64 v[248:249], s[10:11], 0, v[250:251]
	global_load_dwordx4 v[146:149], v[248:249], off
	v_lshl_add_u64 v[248:249], s[46:47], 0, v[250:251]
	global_load_dwordx4 v[150:153], v[248:249], off
	v_lshl_add_u64 v[248:249], s[50:51], 0, v[250:251]
	global_load_dwordx4 v[162:165], v[248:249], off
	global_load_dwordx4 v[166:169], v[90:91], off offset:1024
	v_or_b32_e32 v250, 0x800, v96
	v_lshl_add_u64 v[248:249], s[22:23], 0, v[250:251]
	global_load_dwordx4 v[170:173], v[248:249], off
	v_lshl_add_u64 v[248:249], s[10:11], 0, v[250:251]
	global_load_dwordx4 v[174:177], v[248:249], off
	v_lshl_add_u64 v[248:249], s[46:47], 0, v[250:251]
	global_load_dwordx4 v[178:181], v[248:249], off
	v_lshl_add_u64 v[248:249], s[50:51], 0, v[250:251]
	global_load_dwordx4 v[182:185], v[248:249], off
	global_load_dwordx4 v[186:189], v[90:91], off offset:2048
	v_or_b32_e32 v250, 0xc00, v96
	v_lshl_add_u64 v[248:249], s[22:23], 0, v[250:251]
	global_load_dwordx4 v[216:219], v[248:249], off
	v_lshl_add_u64 v[248:249], s[10:11], 0, v[250:251]
	global_load_dwordx4 v[220:223], v[248:249], off
	v_lshl_add_u64 v[248:249], s[46:47], 0, v[250:251]
	global_load_dwordx4 v[224:227], v[248:249], off
	v_lshl_add_u64 v[248:249], s[50:51], 0, v[250:251]
	global_load_dwordx4 v[228:231], v[248:249], off
	global_load_dwordx4 v[232:235], v[90:91], off offset:3072
	s_waitcnt vmcnt(15)
	v_pk_add_f32 v[236:237], v[122:123], v[126:127]
	v_pk_add_f32 v[238:239], v[124:125], v[128:129]
	v_pk_add_f32 v[240:241], v[130:131], v[134:135]
	v_pk_add_f32 v[242:243], v[132:133], v[136:137]
	v_pk_add_f32 v[236:237], v[236:237], v[240:241]
	v_pk_add_f32 v[238:239], v[238:239], v[242:243]
	v_pk_fma_f32 v[14:15], v[140:141], v[238:239], v[14:15]
	v_pk_fma_f32 v[12:13], v[138:139], v[236:237], v[12:13]
	v_lshl_add_u64 v[248:249], s[26:27], 0, v[96:97]
	global_store_dwordx4 v[248:249], v[12:15], off
	s_waitcnt vmcnt(11)
	v_pk_add_f32 v[236:237], v[142:143], v[146:147]
	v_pk_add_f32 v[238:239], v[144:145], v[148:149]
	v_pk_add_f32 v[240:241], v[150:151], v[162:163]
	v_pk_add_f32 v[242:243], v[152:153], v[164:165]
	v_pk_add_f32 v[236:237], v[236:237], v[240:241]
	v_pk_add_f32 v[238:239], v[238:239], v[242:243]
	v_pk_fma_f32 v[10:11], v[168:169], v[238:239], v[10:11]
	v_pk_fma_f32 v[8:9], v[166:167], v[236:237], v[8:9]
	v_or_b32_e32 v250, 0x400, v96
	v_lshl_add_u64 v[248:249], s[26:27], 0, v[250:251]
	global_store_dwordx4 v[248:249], v[8:11], off
	s_waitcnt vmcnt(7)
	v_pk_add_f32 v[236:237], v[170:171], v[174:175]
	v_pk_add_f32 v[238:239], v[172:173], v[176:177]
	v_pk_add_f32 v[240:241], v[178:179], v[182:183]
	v_pk_add_f32 v[242:243], v[180:181], v[184:185]
	v_pk_add_f32 v[236:237], v[236:237], v[240:241]
	v_pk_add_f32 v[238:239], v[238:239], v[242:243]
	v_pk_fma_f32 v[6:7], v[188:189], v[238:239], v[6:7]
	v_pk_fma_f32 v[4:5], v[186:187], v[236:237], v[4:5]
	v_or_b32_e32 v250, 0x800, v96
	v_lshl_add_u64 v[248:249], s[26:27], 0, v[250:251]
	global_store_dwordx4 v[248:249], v[4:7], off
	s_waitcnt vmcnt(3)
	v_pk_add_f32 v[236:237], v[216:217], v[220:221]
	v_pk_add_f32 v[238:239], v[218:219], v[222:223]
	v_pk_add_f32 v[240:241], v[224:225], v[228:229]
	v_pk_add_f32 v[242:243], v[226:227], v[230:231]
	v_pk_add_f32 v[236:237], v[236:237], v[240:241]
	v_pk_add_f32 v[238:239], v[238:239], v[242:243]
	v_pk_fma_f32 v[2:3], v[234:235], v[238:239], v[2:3]
	v_pk_fma_f32 v[0:1], v[232:233], v[236:237], v[0:1]
	v_or_b32_e32 v250, 0xc00, v96
	v_lshl_add_u64 v[248:249], s[26:27], 0, v[250:251]
	global_store_dwordx4 v[248:249], v[0:3], off
	s_branch .LBB0_1137
